# in-proj epilogue: never-taken rsq denormal guard removed at 8 sites (argument >= 1e-6)
# baseline (speedup 1.0000x reference)
.Lsw_skip_inproj:
	v_bfe_u32 v165, v167, 4, 2
	v_lshlrev_b32_e32 v168, 3, v165
	v_or_b32_e32 v169, s59, v168
	s_mov_b64 s[28:29], -1
	s_cmp_gt_i32 s26, 1
	s_waitcnt vmcnt(0)
	v_ffbh_u32_e32 v146, v145
	v_min_u32_e32 v146, 32, v146
	v_lshlrev_b64 v[144:145], v146, v[144:145]
	v_min_u32_e32 v144, 1, v144
	v_or_b32_e32 v144, v145, v144
	v_cvt_f32_u32_e32 v144, v144
	v_sub_u32_e32 v145, 32, v146
	v_ldexp_f32 v144, v144, v145
	v_fmamk_f32 v144, v144, 0x31800000, v219
	v_rsq_f32_e32 v144, v144
	s_nop 0
	v_mul_f32_e32 v145, 0x45800000, v144
	v_mov_b32_e32 v146, v144
	v_pk_mul_f32 v[128:129], v[128:129], v[146:147] op_sel_hi:[1,0]
	v_pk_mul_f32 v[126:127], v[126:127], v[146:147] op_sel_hi:[1,0]
	v_pk_mul_f32 v[124:125], v[124:125], v[146:147] op_sel_hi:[1,0]
	v_pk_mul_f32 v[122:123], v[122:123], v[146:147] op_sel_hi:[1,0]
	v_pk_mul_f32 v[120:121], v[120:121], v[146:147] op_sel_hi:[1,0]
	v_pk_mul_f32 v[144:145], v[118:119], v[146:147] op_sel_hi:[1,0]
	v_pk_mul_f32 v[116:117], v[116:117], v[146:147] op_sel_hi:[1,0]
	v_pk_mul_f32 v[118:119], v[114:115], v[146:147] op_sel_hi:[1,0]
	v_mov_b64_e32 v[146:147], v[176:177]
	v_or_b32_e32 v114, 16, v142
	v_ashrrev_i32_e32 v115, 31, v114
	s_nop 0
	v_ffbh_u32_e32 v148, v147
	v_min_u32_e32 v148, 32, v148
	v_lshlrev_b64 v[146:147], v148, v[146:147]
	v_min_u32_e32 v146, 1, v146
	v_or_b32_e32 v146, v147, v146
	v_cvt_f32_u32_e32 v146, v146
	v_sub_u32_e32 v147, 32, v148
	v_ldexp_f32 v146, v146, v147
	v_fmamk_f32 v146, v146, 0x31800000, v219
	v_rsq_f32_e32 v146, v146
	s_nop 0
	v_mul_f32_e32 v147, 0x45800000, v146
	v_mov_b32_e32 v148, v146
	v_pk_mul_f32 v[112:113], v[112:113], v[148:149] op_sel_hi:[1,0]
	v_pk_mul_f32 v[110:111], v[110:111], v[148:149] op_sel_hi:[1,0]
	v_pk_mul_f32 v[108:109], v[108:109], v[148:149] op_sel_hi:[1,0]
	v_pk_mul_f32 v[106:107], v[106:107], v[148:149] op_sel_hi:[1,0]
	v_pk_mul_f32 v[104:105], v[104:105], v[148:149] op_sel_hi:[1,0]
	v_pk_mul_f32 v[146:147], v[102:103], v[148:149] op_sel_hi:[1,0]
	v_pk_mul_f32 v[100:101], v[100:101], v[148:149] op_sel_hi:[1,0]
	v_pk_mul_f32 v[102:103], v[98:99], v[148:149] op_sel_hi:[1,0]
	v_mov_b64_e32 v[148:149], v[178:179]
	v_or_b32_e32 v98, 32, v142
	v_ashrrev_i32_e32 v99, 31, v98
	s_nop 0
	v_ffbh_u32_e32 v150, v149
	v_min_u32_e32 v150, 32, v150
	v_lshlrev_b64 v[148:149], v150, v[148:149]
	v_min_u32_e32 v148, 1, v148
	v_or_b32_e32 v148, v149, v148
	v_cvt_f32_u32_e32 v148, v148
	v_sub_u32_e32 v149, 32, v150
	v_ldexp_f32 v148, v148, v149
	v_fmamk_f32 v148, v148, 0x31800000, v219
	v_rsq_f32_e32 v148, v148
	s_nop 0
	v_mul_f32_e32 v149, 0x45800000, v148
	v_mov_b32_e32 v150, v148
	v_pk_mul_f32 v[96:97], v[96:97], v[150:151] op_sel_hi:[1,0]
	v_pk_mul_f32 v[94:95], v[94:95], v[150:151] op_sel_hi:[1,0]
	v_pk_mul_f32 v[92:93], v[92:93], v[150:151] op_sel_hi:[1,0]
	v_pk_mul_f32 v[90:91], v[90:91], v[150:151] op_sel_hi:[1,0]
	v_pk_mul_f32 v[88:89], v[88:89], v[150:151] op_sel_hi:[1,0]
	v_pk_mul_f32 v[148:149], v[86:87], v[150:151] op_sel_hi:[1,0]
	v_pk_mul_f32 v[84:85], v[84:85], v[150:151] op_sel_hi:[1,0]
	v_pk_mul_f32 v[86:87], v[82:83], v[150:151] op_sel_hi:[1,0]
	v_mov_b64_e32 v[150:151], v[180:181]
	v_or_b32_e32 v82, 48, v142
	v_ashrrev_i32_e32 v83, 31, v82
	s_nop 0
	v_ffbh_u32_e32 v152, v151
	v_min_u32_e32 v152, 32, v152
	v_lshlrev_b64 v[150:151], v152, v[150:151]
	v_min_u32_e32 v150, 1, v150
	v_or_b32_e32 v150, v151, v150
	v_cvt_f32_u32_e32 v150, v150
	v_sub_u32_e32 v151, 32, v152
	v_ldexp_f32 v150, v150, v151
	v_fmamk_f32 v150, v150, 0x31800000, v219
	v_rsq_f32_e32 v150, v150
	s_nop 0
	v_mul_f32_e32 v151, 0x45800000, v150
	v_mov_b32_e32 v152, v150
	v_pk_mul_f32 v[80:81], v[80:81], v[152:153] op_sel_hi:[1,0]
	v_pk_mul_f32 v[78:79], v[78:79], v[152:153] op_sel_hi:[1,0]
	v_pk_mul_f32 v[76:77], v[76:77], v[152:153] op_sel_hi:[1,0]
	v_pk_mul_f32 v[74:75], v[74:75], v[152:153] op_sel_hi:[1,0]
	v_pk_mul_f32 v[72:73], v[72:73], v[152:153] op_sel_hi:[1,0]
	v_pk_mul_f32 v[150:151], v[70:71], v[152:153] op_sel_hi:[1,0]
	v_pk_mul_f32 v[68:69], v[68:69], v[152:153] op_sel_hi:[1,0]
	v_pk_mul_f32 v[70:71], v[66:67], v[152:153] op_sel_hi:[1,0]
	v_mov_b64_e32 v[152:153], v[182:183]
	v_add_u32_e32 v66, 0x80, v142
	v_ashrrev_i32_e32 v67, 31, v66
	s_nop 0
	v_ffbh_u32_e32 v154, v153
	v_min_u32_e32 v154, 32, v154
	v_lshlrev_b64 v[152:153], v154, v[152:153]
	v_min_u32_e32 v152, 1, v152
	v_or_b32_e32 v152, v153, v152
	v_cvt_f32_u32_e32 v152, v152
	v_sub_u32_e32 v153, 32, v154
	v_ldexp_f32 v152, v152, v153
	v_fmamk_f32 v152, v152, 0x31800000, v219
	v_rsq_f32_e32 v152, v152
	s_nop 0
	v_mul_f32_e32 v153, 0x45800000, v152
	v_mov_b32_e32 v154, v152
	v_pk_mul_f32 v[64:65], v[64:65], v[154:155] op_sel_hi:[1,0]
	v_pk_mul_f32 v[62:63], v[62:63], v[154:155] op_sel_hi:[1,0]
	v_pk_mul_f32 v[60:61], v[60:61], v[154:155] op_sel_hi:[1,0]
	v_pk_mul_f32 v[58:59], v[58:59], v[154:155] op_sel_hi:[1,0]
	v_pk_mul_f32 v[56:57], v[56:57], v[154:155] op_sel_hi:[1,0]
	v_pk_mul_f32 v[152:153], v[54:55], v[154:155] op_sel_hi:[1,0]
	v_pk_mul_f32 v[52:53], v[52:53], v[154:155] op_sel_hi:[1,0]
	v_pk_mul_f32 v[54:55], v[50:51], v[154:155] op_sel_hi:[1,0]
	v_mov_b64_e32 v[154:155], v[184:185]
	v_add_u32_e32 v50, 0x90, v142
	v_ashrrev_i32_e32 v51, 31, v50
	s_nop 0
	v_ffbh_u32_e32 v156, v155
	v_min_u32_e32 v156, 32, v156
	v_lshlrev_b64 v[154:155], v156, v[154:155]
	v_min_u32_e32 v154, 1, v154
	v_or_b32_e32 v154, v155, v154
	v_cvt_f32_u32_e32 v154, v154
	v_sub_u32_e32 v155, 32, v156
	v_ldexp_f32 v154, v154, v155
	v_fmamk_f32 v154, v154, 0x31800000, v219
	v_rsq_f32_e32 v154, v154
	s_nop 0
	v_mul_f32_e32 v155, 0x45800000, v154
	v_mov_b32_e32 v156, v154
	v_pk_mul_f32 v[48:49], v[48:49], v[156:157] op_sel_hi:[1,0]
	v_pk_mul_f32 v[46:47], v[46:47], v[156:157] op_sel_hi:[1,0]
	v_pk_mul_f32 v[44:45], v[44:45], v[156:157] op_sel_hi:[1,0]
	v_pk_mul_f32 v[42:43], v[42:43], v[156:157] op_sel_hi:[1,0]
	v_pk_mul_f32 v[40:41], v[40:41], v[156:157] op_sel_hi:[1,0]
	v_pk_mul_f32 v[154:155], v[38:39], v[156:157] op_sel_hi:[1,0]
	v_pk_mul_f32 v[36:37], v[36:37], v[156:157] op_sel_hi:[1,0]
	v_pk_mul_f32 v[38:39], v[34:35], v[156:157] op_sel_hi:[1,0]
	v_mov_b64_e32 v[156:157], v[186:187]
	v_add_u32_e32 v34, 0xa0, v142
	v_mov_b64_e32 v[158:159], v[188:189]
	v_ashrrev_i32_e32 v35, 31, v34
	s_nop 0
	v_ffbh_u32_e32 v160, v157
	v_min_u32_e32 v160, 32, v160
	v_lshlrev_b64 v[156:157], v160, v[156:157]
	v_min_u32_e32 v156, 1, v156
	v_or_b32_e32 v156, v157, v156
	v_cvt_f32_u32_e32 v156, v156
	v_sub_u32_e32 v157, 32, v160
	v_ldexp_f32 v156, v156, v157
	v_fmamk_f32 v156, v156, 0x31800000, v219
	v_rsq_f32_e32 v156, v156
	s_nop 0
	v_mul_f32_e32 v157, 0x45800000, v156
	v_mov_b32_e32 v160, v156
	v_pk_mul_f32 v[32:33], v[32:33], v[160:161] op_sel_hi:[1,0]
	v_pk_mul_f32 v[30:31], v[30:31], v[160:161] op_sel_hi:[1,0]
	v_pk_mul_f32 v[28:29], v[28:29], v[160:161] op_sel_hi:[1,0]
	v_pk_mul_f32 v[26:27], v[26:27], v[160:161] op_sel_hi:[1,0]
	v_pk_mul_f32 v[24:25], v[24:25], v[160:161] op_sel_hi:[1,0]
	v_pk_mul_f32 v[156:157], v[22:23], v[160:161] op_sel_hi:[1,0]
	v_pk_mul_f32 v[20:21], v[20:21], v[160:161] op_sel_hi:[1,0]
	v_pk_mul_f32 v[22:23], v[18:19], v[160:161] op_sel_hi:[1,0]
	s_nop 0
	v_ffbh_u32_e32 v160, v159
	v_min_u32_e32 v160, 32, v160
	v_lshlrev_b64 v[158:159], v160, v[158:159]
	v_min_u32_e32 v158, 1, v158
	v_or_b32_e32 v158, v159, v158
	v_cvt_f32_u32_e32 v158, v158
	v_sub_u32_e32 v159, 32, v160
	v_add_u32_e32 v18, 0xb0, v142
	v_ashrrev_i32_e32 v19, 31, v18
	v_ldexp_f32 v158, v158, v159
	v_fmamk_f32 v158, v158, 0x31800000, v219
	v_rsq_f32_e32 v158, v158
	s_nop 0
	v_mul_f32_e32 v159, 0x45800000, v158
	v_pk_mul_f32 v[16:17], v[16:17], v[158:159] op_sel_hi:[1,0]
	v_pk_mul_f32 v[14:15], v[14:15], v[158:159] op_sel_hi:[1,0]
	v_pk_mul_f32 v[12:13], v[12:13], v[158:159] op_sel_hi:[1,0]
	v_pk_mul_f32 v[10:11], v[10:11], v[158:159] op_sel_hi:[1,0]
	v_pk_mul_f32 v[8:9], v[8:9], v[158:159] op_sel_hi:[1,0]
	v_pk_mul_f32 v[6:7], v[6:7], v[158:159] op_sel_hi:[1,0]
	v_pk_mul_f32 v[4:5], v[4:5], v[158:159] op_sel_hi:[1,0]
	v_pk_mul_f32 v[2:3], v[2:3], v[158:159] op_sel_hi:[1,0]
	s_cbranch_scc0 .LBB0_339
	s_cmp_eq_u32 s26, 4
	s_cselect_b64 s[28:29], -1, 0
	s_cmp_lg_u32 s26, 4
	s_cselect_b64 s[30:31], -1, 0
	s_and_b32 s19, s26, 0x7ffffffe
	s_cmp_lg_u32 s19, 6
	s_cselect_b64 s[34:35], -1, 0
	s_and_b64 s[34:35], s[30:31], s[34:35]
	s_mov_b64 s[30:31], -1
	s_and_b64 vcc, exec, s[34:35]
	s_cbranch_vccz .LBB0_336
	s_cmp_lt_u32 s26, 8
	s_cbranch_scc0 .LBB0_333
	s_cmp_eq_u32 s26, 3
	s_movk_i32 s19, 0x300
	s_cselect_b32 s19, 0x200, s19
	s_cmp_lg_u32 s26, 2
	v_lshlrev_b64 v[158:159], 11, v[142:143]
	s_cselect_b32 s19, s19, 0x100
	v_lshl_add_u64 v[158:159], s[10:11], 0, v[158:159]
	s_lshl_b32 s80, s19, 1
	v_lshl_add_u64 v[158:159], v[158:159], 0, s[80:81]
	v_lshlrev_b32_e32 v162, 1, v169
	v_mov_b32_e32 v163, v0
	v_lshl_add_u64 v[170:171], v[158:159], 0, v[162:163]
	v_cvt_pk_bf16_f32 v158, v126, v127
	v_cvt_pk_bf16_f32 v159, v128, v129
	v_cvt_pk_bf16_f32 v160, v122, v123
	v_cvt_pk_bf16_f32 v161, v124, v125
	global_store_dwordx4 v[170:171], v[158:161], off
	s_mov_b64 s[30:31], 0
	s_nop 0
	v_cvt_pk_bf16_f32 v158, v144, v145
	v_cvt_pk_bf16_f32 v159, v120, v121
	v_cvt_pk_bf16_f32 v160, v118, v119
	v_cvt_pk_bf16_f32 v161, v116, v117
	global_store_dwordx4 v[170:171], v[158:161], off offset:256
	s_nop 1
	v_lshlrev_b64 v[158:159], 11, v[114:115]
	v_lshl_add_u64 v[158:159], s[10:11], 0, v[158:159]
	v_lshl_add_u64 v[158:159], v[158:159], 0, s[80:81]
	v_lshl_add_u64 v[170:171], v[158:159], 0, v[162:163]
	v_cvt_pk_bf16_f32 v158, v110, v111
	v_cvt_pk_bf16_f32 v159, v112, v113
	v_cvt_pk_bf16_f32 v160, v106, v107
	v_cvt_pk_bf16_f32 v161, v108, v109
	global_store_dwordx4 v[170:171], v[158:161], off
	s_nop 1
	v_cvt_pk_bf16_f32 v158, v146, v147
	v_cvt_pk_bf16_f32 v159, v104, v105
	v_cvt_pk_bf16_f32 v160, v102, v103
	v_cvt_pk_bf16_f32 v161, v100, v101
	global_store_dwordx4 v[170:171], v[158:161], off offset:256
	s_nop 1
	v_lshlrev_b64 v[158:159], 11, v[98:99]
	v_lshl_add_u64 v[158:159], s[10:11], 0, v[158:159]
	v_lshl_add_u64 v[158:159], v[158:159], 0, s[80:81]
	v_lshl_add_u64 v[170:171], v[158:159], 0, v[162:163]
	v_cvt_pk_bf16_f32 v158, v94, v95
	v_cvt_pk_bf16_f32 v159, v96, v97
	v_cvt_pk_bf16_f32 v160, v90, v91
	v_cvt_pk_bf16_f32 v161, v92, v93
	global_store_dwordx4 v[170:171], v[158:161], off
	s_nop 1
	v_cvt_pk_bf16_f32 v158, v148, v149
	v_cvt_pk_bf16_f32 v159, v88, v89
	v_cvt_pk_bf16_f32 v160, v86, v87
	v_cvt_pk_bf16_f32 v161, v84, v85
	global_store_dwordx4 v[170:171], v[158:161], off offset:256
	s_nop 1
	v_lshlrev_b64 v[158:159], 11, v[82:83]
	v_lshl_add_u64 v[158:159], s[10:11], 0, v[158:159]
	v_lshl_add_u64 v[158:159], v[158:159], 0, s[80:81]
	v_lshl_add_u64 v[170:171], v[158:159], 0, v[162:163]
	v_cvt_pk_bf16_f32 v158, v78, v79
	v_cvt_pk_bf16_f32 v159, v80, v81
	v_cvt_pk_bf16_f32 v160, v74, v75
	v_cvt_pk_bf16_f32 v161, v76, v77
	global_store_dwordx4 v[170:171], v[158:161], off
	s_nop 1
	v_cvt_pk_bf16_f32 v158, v150, v151
	v_cvt_pk_bf16_f32 v159, v72, v73
	v_cvt_pk_bf16_f32 v160, v70, v71
	v_cvt_pk_bf16_f32 v161, v68, v69
	global_store_dwordx4 v[170:171], v[158:161], off offset:256
	s_nop 1
	v_lshlrev_b64 v[158:159], 11, v[66:67]
	v_lshl_add_u64 v[158:159], s[10:11], 0, v[158:159]
	v_lshl_add_u64 v[158:159], v[158:159], 0, s[80:81]
	v_lshl_add_u64 v[170:171], v[158:159], 0, v[162:163]
	v_cvt_pk_bf16_f32 v158, v62, v63
	v_cvt_pk_bf16_f32 v159, v64, v65
	v_cvt_pk_bf16_f32 v160, v58, v59
	v_cvt_pk_bf16_f32 v161, v60, v61
	global_store_dwordx4 v[170:171], v[158:161], off
	s_nop 1
	v_cvt_pk_bf16_f32 v158, v152, v153
	v_cvt_pk_bf16_f32 v159, v56, v57
	v_cvt_pk_bf16_f32 v160, v54, v55
	v_cvt_pk_bf16_f32 v161, v52, v53
	global_store_dwordx4 v[170:171], v[158:161], off offset:256
	s_nop 1
	v_lshlrev_b64 v[158:159], 11, v[50:51]
	v_lshl_add_u64 v[158:159], s[10:11], 0, v[158:159]
	v_lshl_add_u64 v[158:159], v[158:159], 0, s[80:81]
	v_lshl_add_u64 v[170:171], v[158:159], 0, v[162:163]
	v_cvt_pk_bf16_f32 v158, v46, v47
	v_cvt_pk_bf16_f32 v159, v48, v49
	v_cvt_pk_bf16_f32 v160, v42, v43
	v_cvt_pk_bf16_f32 v161, v44, v45
	global_store_dwordx4 v[170:171], v[158:161], off
	s_nop 1
	v_cvt_pk_bf16_f32 v158, v154, v155
	v_cvt_pk_bf16_f32 v159, v40, v41
	v_cvt_pk_bf16_f32 v160, v38, v39
	v_cvt_pk_bf16_f32 v161, v36, v37
	global_store_dwordx4 v[170:171], v[158:161], off offset:256
	s_nop 1
	v_lshlrev_b64 v[158:159], 11, v[34:35]
	v_lshl_add_u64 v[158:159], s[10:11], 0, v[158:159]
	v_lshl_add_u64 v[158:159], v[158:159], 0, s[80:81]
	v_lshl_add_u64 v[170:171], v[158:159], 0, v[162:163]
	v_cvt_pk_bf16_f32 v158, v30, v31
	v_cvt_pk_bf16_f32 v159, v32, v33
	v_cvt_pk_bf16_f32 v160, v26, v27
	v_cvt_pk_bf16_f32 v161, v28, v29
	global_store_dwordx4 v[170:171], v[158:161], off
	s_nop 1
	v_cvt_pk_bf16_f32 v158, v156, v157
	v_cvt_pk_bf16_f32 v159, v24, v25
	v_cvt_pk_bf16_f32 v160, v22, v23
	v_cvt_pk_bf16_f32 v161, v20, v21
	global_store_dwordx4 v[170:171], v[158:161], off offset:256
	s_nop 1
	v_lshlrev_b64 v[158:159], 11, v[18:19]
	v_lshl_add_u64 v[158:159], s[10:11], 0, v[158:159]
	v_lshl_add_u64 v[158:159], v[158:159], 0, s[80:81]
	v_lshl_add_u64 v[162:163], v[158:159], 0, v[162:163]
	v_cvt_pk_bf16_f32 v158, v14, v15
	v_cvt_pk_bf16_f32 v159, v16, v17
	v_cvt_pk_bf16_f32 v160, v10, v11
	v_cvt_pk_bf16_f32 v161, v12, v13
	global_store_dwordx4 v[162:163], v[158:161], off
	s_nop 1
	v_cvt_pk_bf16_f32 v158, v6, v7
	v_cvt_pk_bf16_f32 v159, v8, v9
	v_cvt_pk_bf16_f32 v160, v2, v3
	v_cvt_pk_bf16_f32 v161, v4, v5
	global_store_dwordx4 v[162:163], v[158:161], off offset:256
